# ConvGLU epilogue: neighbour-row LDS reads of interior row groups without the wave-uniform flag tests and branches
# speedup vs baseline: 1.0287x; 1.0001x over previous
;     __device__ __forceinline__ void run_glu(const f32x4 (&acc)[2][2][4][2], const pg8::Unit& u, int wr, int wc, int fr, int fq) const {
;     ...
;         for (int bj = 0; bj < 2; ++bj) {
;             int col = u.pn * 256 + bj * 128 + wc * 32 + 8 * fq; asm volatile("" : "+v"(col)); const int ch = (col >> 3) * 4;
;             const f32x4 c0 = *(const f32x4*)(f0 + ch), c1 = *(const f32x4*)(f0 + DFF + ch), c2 = *(const f32x4*)(f0 + 2 * DFF + ch), cb = *(const f32x4*)(f1 + ch);
; #pragma unroll
;             for (int ai = 0; ai < 2; ++ai)
; #pragma unroll
;                 for (int m = 0; m < 4; ++m) { const int g = ai * 8 + wr * 4 + m;
;                     const int row = u.pm * 256 + g * 16 + fro;
;                     const f32x4 gt = acc[ai][bj][m][0], vl = acc[ai][bj][m][1];
;                     f32x4 gp, gn;
; #pragma unroll
;                     for (int i = 0; i < 4; ++i) { gp[i] = __int_as_float(__builtin_amdgcn_update_dpp(0, __float_as_int(gt[i]), 0x111, 0xF, 0xF, true));
;                                                   gn[i] = __int_as_float(__builtin_amdgcn_update_dpp(0, __float_as_int(gt[i]), 0x101, 0xF, 0xF, true)); }
;                     if (fr == 0) {
;                         if (g > 0) gp = *(const LAS f32x4*)(B + ((g - 1) * 2 + 1) * 128 + lidx + bj * 16);
;                         else if (!tfirst) { const u32x2 w = *(const u32x2*)(VFp + (size_t)(2 * (u.pm - 1)) * (2 * DFF) + col); gp = (f32x4){bflo(w.x), bfhi(w.x), bflo(w.y), bfhi(w.y)}; }
;                         else gp = (f32x4){0.f, 0.f, 0.f, 0.f};
;                     }
;                     if (fr == 15) {
;                         if (g < 15) gn = *(const LAS f32x4*)(B + ((g + 1) * 2 + 0) * 128 + lidx + bj * 16);
;                         else if (!tlast) { const u32x2 w = *(const u32x2*)(VFp + (size_t)(2 * u.pm + 1) * (2 * DFF) + col); gn = (f32x4){bflo(w.x), bfhi(w.x), bflo(w.y), bfhi(w.y)}; }
;                         else gn = (f32x4){0.f, 0.f, 0.f, 0.f};
;                     }
;                     float o[4];
; #pragma unroll
;                     for (int i = 0; i < 4; ++i) { const float x = gp[i] * c0[i] + gt[i] * c1[i] + gn[i] * c2[i] + cb[i]; o[i] = x * __builtin_amdgcn_rcpf(1.f + __expf(-x)) * vl[i]; }
;                     u32x2 w; w.x = cvt_pk_bf16(o[0], o[1]); w.y = cvt_pk_bf16(o[2], o[3]);
;                     *(u32x2*)(O + (size_t)row * DFF + ch) = w;
.LBB0_443:
	s_or_b64 exec, exec, s[2:3]
	s_bitset0_b32 s16, 4
	s_cmp_lg_u32 s16, 0
	s_cselect_b64 s[2:3], -1, 0
	s_mov_b64 s[14:15], exec
	v_readlane_b32 s16, v255, 46
	v_readlane_b32 s17, v255, 47
	s_and_b64 s[16:17], s[14:15], s[16:17]
	s_mov_b64 exec, s[16:17]
.LBB0_448:
	ds_read_b128 v[150:153], v188 offset:1024
	s_waitcnt lgkmcnt(0)
	v_mov_b32_e32 v169, v152
	v_mov_b32_e32 v171, v150
.LBB0_449:
	s_or_b64 exec, exec, s[14:15]
	v_mov_b32_e32 v172, v126
	s_waitcnt vmcnt(0)
	v_mov_b32_e32 v173, v138
	v_mov_b32_e32 v170, v134
	v_pk_mul_f32 v[170:171], v[172:173], v[170:171]
	v_mov_b32_e32 v168, v136
	s_waitcnt lgkmcnt(0)
	v_fma_f32 v146, v130, v146, v170
	v_add_f32_e32 v146, v146, v171
	v_add_f32_e32 v146, v142, v146
	v_mul_f32_e32 v150, 0xbfb8aa3b, v146
	v_exp_f32_e32 v150, v150
	v_mov_b32_e32 v170, v127
	v_mov_b32_e32 v171, v139
	s_lshl_b32 s67, s5, 8
	v_add_f32_e32 v150, 1.0, v150
	v_rcp_f32_e32 v152, v150
	v_mov_b32_e32 v150, v135
	v_pk_mul_f32 v[150:151], v[170:171], v[150:151]
	v_readlane_b32 s14, v254, 44
	v_fma_f32 v147, v131, v147, v150
	v_add_f32_e32 v147, v147, v151
	v_add_f32_e32 v150, v143, v147
	v_mul_f32_e32 v147, 0xbfb8aa3b, v150
	v_exp_f32_e32 v147, v147
	v_mul_f32_e32 v146, v146, v152
	v_mul_f32_e32 v170, v122, v146
	v_mov_b32_e32 v152, v137
	v_add_f32_e32 v146, 1.0, v147
	v_rcp_f32_e32 v171, v146
	v_mov_b32_e32 v146, v128
	v_mov_b32_e32 v147, v140
	v_pk_mul_f32 v[146:147], v[146:147], v[168:169]
	s_add_i32 s14, s67, s14
	v_fma_f32 v146, v132, v148, v146
	v_add_f32_e32 v146, v146, v147
	v_add_f32_e32 v148, v144, v146
	v_mul_f32_e32 v146, 0xbfb8aa3b, v148
	v_exp_f32_e32 v168, v146
	v_mov_b32_e32 v146, v129
	v_mov_b32_e32 v147, v141
	v_pk_mul_f32 v[146:147], v[146:147], v[152:153]
	v_add_u32_e32 v151, s14, v189
	v_fma_f32 v146, v133, v149, v146
	v_add_f32_e32 v146, v146, v147
	v_add_f32_e32 v146, v145, v146
	v_mul_f32_e32 v147, 0xbfb8aa3b, v146
	v_exp_f32_e32 v147, v147
	v_mul_f32_e32 v149, v150, v171
	v_add_f32_e32 v150, 1.0, v168
	v_rcp_f32_e32 v150, v150
	v_add_f32_e32 v147, 1.0, v147
	v_rcp_f32_e32 v147, v147
	v_mul_f32_e32 v149, v123, v149
	v_mul_f32_e32 v148, v148, v150
	v_mul_f32_e32 v148, v124, v148
	v_mul_f32_e32 v146, v146, v147
	v_mul_f32_e32 v147, v125, v146
	v_cvt_pk_bf16_f32 v146, v170, v149
	v_cvt_pk_bf16_f32 v147, v148, v147
	v_mov_b64_e32 v[148:149], s[86:87]
	s_movk_i32 s14, 0x1600
	v_mad_i64_i32 v[168:169], s[14:15], v151, s14, v[148:149]
	v_readlane_b32 s14, v254, 56
	v_readlane_b32 s15, v254, 57
	v_lshl_add_u64 v[148:149], v[166:167], 1, v[168:169]
	global_store_dwordx2 v[148:149], v[146:147], off
	v_cndmask_b32_e64 v150, 0, 1, s[14:15]
	v_mov_b32_dpp v146, v110 row_shr:1 row_mask:0xf bank_mask:0xf bound_ctrl:1
	v_mov_b32_dpp v173, v110 row_shl:1 row_mask:0xf bank_mask:0xf bound_ctrl:1
	v_mov_b32_dpp v147, v111 row_shr:1 row_mask:0xf bank_mask:0xf bound_ctrl:1
	v_mov_b32_dpp v151, v111 row_shl:1 row_mask:0xf bank_mask:0xf bound_ctrl:1
	v_mov_b32_dpp v148, v112 row_shr:1 row_mask:0xf bank_mask:0xf bound_ctrl:1
	v_mov_b32_dpp v171, v112 row_shl:1 row_mask:0xf bank_mask:0xf bound_ctrl:1
	v_mov_b32_dpp v149, v113 row_shr:1 row_mask:0xf bank_mask:0xf bound_ctrl:1
	v_mov_b32_dpp v153, v113 row_shl:1 row_mask:0xf bank_mask:0xf bound_ctrl:1
	v_cmp_ne_u32_e64 s[14:15], 1, v150
	s_mov_b64 s[16:17], exec
	v_readlane_b32 s18, v255, 44
	v_readlane_b32 s19, v255, 45
	s_and_b64 s[18:19], s[16:17], s[18:19]
	s_mov_b64 exec, s[18:19]
	v_readlane_b32 s18, v255, 30
	s_nop 1
	v_lshl_add_u32 v146, v186, 2, s18
	ds_read_b128 v[146:149], v146
.LBB0_456:
	s_or_b64 exec, exec, s[16:17]
	v_readlane_b32 s16, v254, 58
	v_readlane_b32 s17, v254, 59
	s_nop 1
	v_cndmask_b32_e64 v150, 0, 1, s[16:17]
	v_cmp_ne_u32_e64 s[20:21], 1, v150
	s_mov_b64 s[16:17], exec
	v_readlane_b32 s18, v255, 46
	v_readlane_b32 s19, v255, 47
	s_and_b64 s[18:19], s[16:17], s[18:19]
	s_mov_b64 exec, s[18:19]
.LBB0_461:
	ds_read_b128 v[150:153], v222 offset:1024
	s_waitcnt lgkmcnt(0)
	v_mov_b32_e32 v171, v152
	v_mov_b32_e32 v173, v150
.LBB0_462:
	s_or_b64 exec, exec, s[16:17]
	v_mov_b32_e32 v174, v110
	v_mov_b32_e32 v175, v138
	v_mov_b32_e32 v172, v134
	v_pk_mul_f32 v[172:173], v[174:175], v[172:173]
	v_mov_b32_e32 v170, v136
	s_waitcnt lgkmcnt(0)
	v_fma_f32 v146, v130, v146, v172
	v_add_f32_e32 v146, v146, v173
	v_add_f32_e32 v146, v142, v146
	v_mul_f32_e32 v150, 0xbfb8aa3b, v146
	v_exp_f32_e32 v150, v150
	v_mov_b32_e32 v172, v111
	v_mov_b32_e32 v173, v139
	v_readlane_b32 s16, v254, 55
	v_add_f32_e32 v150, 1.0, v150
	v_rcp_f32_e32 v152, v150
	v_mov_b32_e32 v150, v135
	v_pk_mul_f32 v[150:151], v[172:173], v[150:151]
	s_add_i32 s16, s67, s16
	v_fma_f32 v147, v131, v147, v150
	v_add_f32_e32 v147, v147, v151
	v_add_f32_e32 v150, v143, v147
	v_mul_f32_e32 v147, 0xbfb8aa3b, v150
	v_exp_f32_e32 v147, v147
	v_mul_f32_e32 v146, v146, v152
	v_mul_f32_e32 v172, v106, v146
	v_mov_b32_e32 v152, v137
	v_add_f32_e32 v146, 1.0, v147
	v_rcp_f32_e32 v173, v146
	v_mov_b32_e32 v146, v112
	v_mov_b32_e32 v147, v140
	v_pk_mul_f32 v[146:147], v[146:147], v[170:171]
	v_add_u32_e32 v151, s16, v189
	v_fma_f32 v146, v132, v148, v146
	v_add_f32_e32 v146, v146, v147
	v_add_f32_e32 v148, v144, v146
	v_mul_f32_e32 v146, 0xbfb8aa3b, v148
	v_exp_f32_e32 v170, v146
	v_mov_b32_e32 v146, v113
	v_mov_b32_e32 v147, v141
	v_pk_mul_f32 v[146:147], v[146:147], v[152:153]
	s_movk_i32 s16, 0x1600
	v_fma_f32 v146, v133, v149, v146
	v_add_f32_e32 v146, v146, v147
	v_add_f32_e32 v146, v145, v146
	v_mul_f32_e32 v147, 0xbfb8aa3b, v146
	v_exp_f32_e32 v147, v147
	v_mul_f32_e32 v149, v150, v173
	v_add_f32_e32 v150, 1.0, v170
	v_rcp_f32_e32 v150, v150
	v_add_f32_e32 v147, 1.0, v147
	v_rcp_f32_e32 v147, v147
	v_mul_f32_e32 v149, v107, v149
	v_mul_f32_e32 v148, v148, v150
	v_mul_f32_e32 v148, v108, v148
	v_mul_f32_e32 v146, v146, v147
	v_mul_f32_e32 v147, v109, v146
	v_cvt_pk_bf16_f32 v146, v172, v149
	v_cvt_pk_bf16_f32 v147, v148, v147
	v_mov_b64_e32 v[148:149], s[86:87]
	v_mad_i64_i32 v[170:171], s[16:17], v151, s16, v[148:149]
	v_lshl_add_u64 v[148:149], v[166:167], 1, v[170:171]
	global_store_dwordx2 v[148:149], v[146:147], off
	v_mov_b32_dpp v146, v92 row_shr:1 row_mask:0xf bank_mask:0xf bound_ctrl:1
	v_mov_b32_dpp v175, v92 row_shl:1 row_mask:0xf bank_mask:0xf bound_ctrl:1
	v_mov_b32_dpp v147, v93 row_shr:1 row_mask:0xf bank_mask:0xf bound_ctrl:1
	v_mov_b32_dpp v151, v93 row_shl:1 row_mask:0xf bank_mask:0xf bound_ctrl:1
	v_mov_b32_dpp v148, v94 row_shr:1 row_mask:0xf bank_mask:0xf bound_ctrl:1
	v_mov_b32_dpp v173, v94 row_shl:1 row_mask:0xf bank_mask:0xf bound_ctrl:1
	v_mov_b32_dpp v149, v95 row_shr:1 row_mask:0xf bank_mask:0xf bound_ctrl:1
	v_mov_b32_dpp v153, v95 row_shl:1 row_mask:0xf bank_mask:0xf bound_ctrl:1
	s_mov_b64 s[16:17], exec
	v_readlane_b32 s18, v255, 44
	v_readlane_b32 s19, v255, 45
	s_and_b64 s[18:19], s[16:17], s[18:19]
	s_mov_b64 exec, s[18:19]
	v_readlane_b32 s18, v255, 32
	s_nop 1
	v_lshl_add_u32 v146, v186, 2, s18
	ds_read_b128 v[146:149], v146
;     __device__ __forceinline__ void run_glu(const f32x4 (&acc)[2][2][4][2], const pg8::Unit& u, int wr, int wc, int fr, int fq) const {
;     ...
;         for (int bj = 0; bj < 2; ++bj) {
;             int col = u.pn * 256 + bj * 128 + wc * 32 + 8 * fq; asm volatile("" : "+v"(col)); const int ch = (col >> 3) * 4;
;             const f32x4 c0 = *(const f32x4*)(f0 + ch), c1 = *(const f32x4*)(f0 + DFF + ch), c2 = *(const f32x4*)(f0 + 2 * DFF + ch), cb = *(const f32x4*)(f1 + ch);
; #pragma unroll
;             for (int ai = 0; ai < 2; ++ai)
; #pragma unroll
;                 for (int m = 0; m < 4; ++m) { const int g = ai * 8 + wr * 4 + m;
;                     const int row = u.pm * 256 + g * 16 + fro;
;                     const f32x4 gt = acc[ai][bj][m][0], vl = acc[ai][bj][m][1];
;                     f32x4 gp, gn;
; #pragma unroll
;                     for (int i = 0; i < 4; ++i) { gp[i] = __int_as_float(__builtin_amdgcn_update_dpp(0, __float_as_int(gt[i]), 0x111, 0xF, 0xF, true));
;                                                   gn[i] = __int_as_float(__builtin_amdgcn_update_dpp(0, __float_as_int(gt[i]), 0x101, 0xF, 0xF, true)); }
;                     if (fr == 0) {
;                         if (g > 0) gp = *(const LAS f32x4*)(B + ((g - 1) * 2 + 1) * 128 + lidx + bj * 16);
;                         else if (!tfirst) { const u32x2 w = *(const u32x2*)(VFp + (size_t)(2 * (u.pm - 1)) * (2 * DFF) + col); gp = (f32x4){bflo(w.x), bfhi(w.x), bflo(w.y), bfhi(w.y)}; }
;                         else gp = (f32x4){0.f, 0.f, 0.f, 0.f};
;                     }
;                     if (fr == 15) {
;                         if (g < 15) gn = *(const LAS f32x4*)(B + ((g + 1) * 2 + 0) * 128 + lidx + bj * 16);
;                         else if (!tlast) { const u32x2 w = *(const u32x2*)(VFp + (size_t)(2 * u.pm + 1) * (2 * DFF) + col); gn = (f32x4){bflo(w.x), bfhi(w.x), bflo(w.y), bfhi(w.y)}; }
;                         else gn = (f32x4){0.f, 0.f, 0.f, 0.f};
;                     }
;                     float o[4];
; #pragma unroll
;                     for (int i = 0; i < 4; ++i) { const float x = gp[i] * c0[i] + gt[i] * c1[i] + gn[i] * c2[i] + cb[i]; o[i] = x * __builtin_amdgcn_rcpf(1.f + __expf(-x)) * vl[i]; }
;                     u32x2 w; w.x = cvt_pk_bf16(o[0], o[1]); w.y = cvt_pk_bf16(o[2], o[3]);
;                     *(u32x2*)(O + (size_t)row * DFF + ch) = w;
.LBB0_469:
	s_or_b64 exec, exec, s[16:17]
	v_readlane_b32 s16, v254, 61
	v_readlane_b32 s17, v254, 62
	s_nop 1
	v_cndmask_b32_e64 v150, 0, 1, s[16:17]
	v_cmp_ne_u32_e64 s[22:23], 1, v150
	s_mov_b64 s[16:17], exec
	v_readlane_b32 s18, v255, 46
	v_readlane_b32 s19, v255, 47
	s_and_b64 s[18:19], s[16:17], s[18:19]
	s_mov_b64 exec, s[18:19]
.LBB0_474:
	ds_read_b128 v[150:153], v221 offset:1024
	s_waitcnt lgkmcnt(0)
	v_mov_b32_e32 v173, v152
	v_mov_b32_e32 v175, v150
.LBB0_475:
	s_or_b64 exec, exec, s[16:17]
	v_mov_b32_e32 v176, v92
	v_mov_b32_e32 v177, v138
	v_mov_b32_e32 v174, v134
	v_pk_mul_f32 v[174:175], v[176:177], v[174:175]
	v_mov_b32_e32 v172, v136
	s_waitcnt lgkmcnt(0)
	v_fma_f32 v146, v130, v146, v174
	v_add_f32_e32 v146, v146, v175
	v_add_f32_e32 v146, v142, v146
	v_mul_f32_e32 v150, 0xbfb8aa3b, v146
	v_exp_f32_e32 v150, v150
	v_mov_b32_e32 v174, v93
	v_mov_b32_e32 v175, v139
	v_readlane_b32 s16, v254, 60
	v_add_f32_e32 v150, 1.0, v150
	v_rcp_f32_e32 v152, v150
	v_mov_b32_e32 v150, v135
	v_pk_mul_f32 v[150:151], v[174:175], v[150:151]
	s_add_i32 s16, s67, s16
	v_fma_f32 v147, v131, v147, v150
	v_add_f32_e32 v147, v147, v151
	v_add_f32_e32 v150, v143, v147
	v_mul_f32_e32 v147, 0xbfb8aa3b, v150
	v_exp_f32_e32 v147, v147
	v_mul_f32_e32 v146, v146, v152
	v_mul_f32_e32 v174, v88, v146
	v_mov_b32_e32 v152, v137
	v_add_f32_e32 v146, 1.0, v147
	v_rcp_f32_e32 v175, v146
	v_mov_b32_e32 v146, v94
	v_mov_b32_e32 v147, v140
	v_pk_mul_f32 v[146:147], v[146:147], v[172:173]
	v_add_u32_e32 v151, s16, v189
	v_fma_f32 v146, v132, v148, v146
	v_add_f32_e32 v146, v146, v147
	v_add_f32_e32 v148, v144, v146
	v_mul_f32_e32 v146, 0xbfb8aa3b, v148
	v_exp_f32_e32 v172, v146
	v_mov_b32_e32 v146, v95
	v_mov_b32_e32 v147, v141
	v_pk_mul_f32 v[146:147], v[146:147], v[152:153]
	s_movk_i32 s16, 0x1600
	v_fma_f32 v146, v133, v149, v146
	v_add_f32_e32 v146, v146, v147
	v_add_f32_e32 v146, v145, v146
	v_mul_f32_e32 v147, 0xbfb8aa3b, v146
	v_exp_f32_e32 v147, v147
	v_mul_f32_e32 v149, v150, v175
	v_add_f32_e32 v150, 1.0, v172
	v_rcp_f32_e32 v150, v150
	v_add_f32_e32 v147, 1.0, v147
	v_rcp_f32_e32 v147, v147
	v_mul_f32_e32 v149, v89, v149
	v_mul_f32_e32 v148, v148, v150
	v_mul_f32_e32 v148, v90, v148
	v_mul_f32_e32 v146, v146, v147
	v_mul_f32_e32 v147, v91, v146
	v_cvt_pk_bf16_f32 v146, v174, v149
	v_cvt_pk_bf16_f32 v147, v148, v147
	v_mov_b64_e32 v[148:149], s[86:87]
	v_mad_i64_i32 v[172:173], s[16:17], v151, s16, v[148:149]
	v_lshl_add_u64 v[148:149], v[166:167], 1, v[172:173]
	global_store_dwordx2 v[148:149], v[146:147], off
	v_mov_b32_dpp v146, v76 row_shr:1 row_mask:0xf bank_mask:0xf bound_ctrl:1
	v_mov_b32_dpp v177, v76 row_shl:1 row_mask:0xf bank_mask:0xf bound_ctrl:1
	v_mov_b32_dpp v147, v77 row_shr:1 row_mask:0xf bank_mask:0xf bound_ctrl:1
	v_mov_b32_dpp v151, v77 row_shl:1 row_mask:0xf bank_mask:0xf bound_ctrl:1
	v_mov_b32_dpp v148, v78 row_shr:1 row_mask:0xf bank_mask:0xf bound_ctrl:1
	v_mov_b32_dpp v175, v78 row_shl:1 row_mask:0xf bank_mask:0xf bound_ctrl:1
	v_mov_b32_dpp v149, v79 row_shr:1 row_mask:0xf bank_mask:0xf bound_ctrl:1
	v_mov_b32_dpp v153, v79 row_shl:1 row_mask:0xf bank_mask:0xf bound_ctrl:1
	s_mov_b64 s[16:17], exec
	v_readlane_b32 s18, v255, 44
	v_readlane_b32 s19, v255, 45
	s_and_b64 s[18:19], s[16:17], s[18:19]
	s_mov_b64 exec, s[18:19]
	v_readlane_b32 s18, v255, 35
	s_nop 1
	v_lshl_add_u32 v146, v186, 2, s18
	ds_read_b128 v[146:149], v146
.LBB0_482:
	s_or_b64 exec, exec, s[16:17]
	v_readlane_b32 s16, v255, 0
	v_readlane_b32 s17, v255, 1
	s_nop 1
	v_cndmask_b32_e64 v150, 0, 1, s[16:17]
	v_cmp_ne_u32_e64 s[24:25], 1, v150
	s_mov_b64 s[16:17], exec
	v_readlane_b32 s18, v255, 46
	v_readlane_b32 s19, v255, 47
	s_and_b64 s[18:19], s[16:17], s[18:19]
	s_mov_b64 exec, s[18:19]
.LBB0_487:
	ds_read_b128 v[150:153], v220 offset:1024
	s_waitcnt lgkmcnt(0)
	v_mov_b32_e32 v175, v152
	v_mov_b32_e32 v177, v150
.LBB0_488:
	s_or_b64 exec, exec, s[16:17]
	v_mov_b32_e32 v178, v76
	v_mov_b32_e32 v179, v138
	v_mov_b32_e32 v176, v134
	v_pk_mul_f32 v[176:177], v[178:179], v[176:177]
	v_mov_b32_e32 v174, v136
	s_waitcnt lgkmcnt(0)
	v_fma_f32 v146, v130, v146, v176
	v_add_f32_e32 v146, v146, v177
	v_add_f32_e32 v146, v142, v146
	v_mul_f32_e32 v150, 0xbfb8aa3b, v146
	v_exp_f32_e32 v150, v150
	v_mov_b32_e32 v176, v77
	v_mov_b32_e32 v177, v139
	v_readlane_b32 s16, v254, 63
	v_add_f32_e32 v150, 1.0, v150
	v_rcp_f32_e32 v152, v150
	v_mov_b32_e32 v150, v135
	v_pk_mul_f32 v[150:151], v[176:177], v[150:151]
	s_add_i32 s16, s67, s16
	v_fma_f32 v147, v131, v147, v150
	v_add_f32_e32 v147, v147, v151
	v_add_f32_e32 v150, v143, v147
	v_mul_f32_e32 v147, 0xbfb8aa3b, v150
	v_exp_f32_e32 v147, v147
	v_mul_f32_e32 v146, v146, v152
	v_mul_f32_e32 v176, v72, v146
	v_mov_b32_e32 v152, v137
	v_add_f32_e32 v146, 1.0, v147
	v_rcp_f32_e32 v177, v146
	v_mov_b32_e32 v146, v78
	v_mov_b32_e32 v147, v140
	v_pk_mul_f32 v[146:147], v[146:147], v[174:175]
	v_add_u32_e32 v151, s16, v189
	v_fma_f32 v146, v132, v148, v146
	v_add_f32_e32 v146, v146, v147
	v_add_f32_e32 v148, v144, v146
	v_mul_f32_e32 v146, 0xbfb8aa3b, v148
	v_exp_f32_e32 v174, v146
	v_mov_b32_e32 v146, v79
	v_mov_b32_e32 v147, v141
	v_pk_mul_f32 v[146:147], v[146:147], v[152:153]
	s_movk_i32 s16, 0x1600
	v_fma_f32 v146, v133, v149, v146
	v_add_f32_e32 v146, v146, v147
	v_add_f32_e32 v146, v145, v146
	v_mul_f32_e32 v147, 0xbfb8aa3b, v146
	v_exp_f32_e32 v147, v147
	v_mul_f32_e32 v149, v150, v177
	v_add_f32_e32 v150, 1.0, v174
	v_rcp_f32_e32 v150, v150
	v_add_f32_e32 v147, 1.0, v147
	v_rcp_f32_e32 v147, v147
	v_mul_f32_e32 v149, v73, v149
	v_mul_f32_e32 v148, v148, v150
	v_mul_f32_e32 v148, v74, v148
	v_mul_f32_e32 v146, v146, v147
	v_mul_f32_e32 v147, v75, v146
	v_cvt_pk_bf16_f32 v146, v176, v149
	v_cvt_pk_bf16_f32 v147, v148, v147
	v_mov_b64_e32 v[148:149], s[86:87]
	v_mad_i64_i32 v[174:175], s[16:17], v151, s16, v[148:149]
	v_lshl_add_u64 v[148:149], v[166:167], 1, v[174:175]
	global_store_dwordx2 v[148:149], v[146:147], off
	v_readlane_b32 s16, v255, 3
	v_readlane_b32 s17, v255, 4
	v_mov_b32_dpp v146, v60 row_shr:1 row_mask:0xf bank_mask:0xf bound_ctrl:1
	v_mov_b32_dpp v179, v60 row_shl:1 row_mask:0xf bank_mask:0xf bound_ctrl:1
	v_cndmask_b32_e64 v150, 0, 1, s[16:17]
	v_mov_b32_dpp v147, v61 row_shr:1 row_mask:0xf bank_mask:0xf bound_ctrl:1
	v_mov_b32_dpp v151, v61 row_shl:1 row_mask:0xf bank_mask:0xf bound_ctrl:1
	v_mov_b32_dpp v148, v62 row_shr:1 row_mask:0xf bank_mask:0xf bound_ctrl:1
	v_mov_b32_dpp v177, v62 row_shl:1 row_mask:0xf bank_mask:0xf bound_ctrl:1
	v_mov_b32_dpp v149, v63 row_shr:1 row_mask:0xf bank_mask:0xf bound_ctrl:1
	v_mov_b32_dpp v153, v63 row_shl:1 row_mask:0xf bank_mask:0xf bound_ctrl:1
	v_cmp_ne_u32_e64 s[26:27], 1, v150
	s_mov_b64 s[16:17], exec
	v_readlane_b32 s18, v255, 44
	v_readlane_b32 s19, v255, 45
	s_and_b64 s[18:19], s[16:17], s[18:19]
	s_mov_b64 exec, s[18:19]
	v_readlane_b32 s18, v255, 37
	s_nop 1
	v_lshl_add_u32 v146, v186, 2, s18
	ds_read_b128 v[146:149], v146
;     __device__ __forceinline__ void run_glu(const f32x4 (&acc)[2][2][4][2], const pg8::Unit& u, int wr, int wc, int fr, int fq) const {
;     ...
;         for (int bj = 0; bj < 2; ++bj) {
;             int col = u.pn * 256 + bj * 128 + wc * 32 + 8 * fq; asm volatile("" : "+v"(col)); const int ch = (col >> 3) * 4;
;             const f32x4 c0 = *(const f32x4*)(f0 + ch), c1 = *(const f32x4*)(f0 + DFF + ch), c2 = *(const f32x4*)(f0 + 2 * DFF + ch), cb = *(const f32x4*)(f1 + ch);
; #pragma unroll
;             for (int ai = 0; ai < 2; ++ai)
; #pragma unroll
;                 for (int m = 0; m < 4; ++m) { const int g = ai * 8 + wr * 4 + m;
;                     const int row = u.pm * 256 + g * 16 + fro;
;                     const f32x4 gt = acc[ai][bj][m][0], vl = acc[ai][bj][m][1];
;                     f32x4 gp, gn;
; #pragma unroll
;                     for (int i = 0; i < 4; ++i) { gp[i] = __int_as_float(__builtin_amdgcn_update_dpp(0, __float_as_int(gt[i]), 0x111, 0xF, 0xF, true));
;                                                   gn[i] = __int_as_float(__builtin_amdgcn_update_dpp(0, __float_as_int(gt[i]), 0x101, 0xF, 0xF, true)); }
;                     if (fr == 0) {
;                         if (g > 0) gp = *(const LAS f32x4*)(B + ((g - 1) * 2 + 1) * 128 + lidx + bj * 16);
;                         else if (!tfirst) { const u32x2 w = *(const u32x2*)(VFp + (size_t)(2 * (u.pm - 1)) * (2 * DFF) + col); gp = (f32x4){bflo(w.x), bfhi(w.x), bflo(w.y), bfhi(w.y)}; }
;                         else gp = (f32x4){0.f, 0.f, 0.f, 0.f};
;                     }
;                     if (fr == 15) {
;                         if (g < 15) gn = *(const LAS f32x4*)(B + ((g + 1) * 2 + 0) * 128 + lidx + bj * 16);
;                         else if (!tlast) { const u32x2 w = *(const u32x2*)(VFp + (size_t)(2 * u.pm + 1) * (2 * DFF) + col); gn = (f32x4){bflo(w.x), bfhi(w.x), bflo(w.y), bfhi(w.y)}; }
;                         else gn = (f32x4){0.f, 0.f, 0.f, 0.f};
;                     }
;                     float o[4];
; #pragma unroll
;                     for (int i = 0; i < 4; ++i) { const float x = gp[i] * c0[i] + gt[i] * c1[i] + gn[i] * c2[i] + cb[i]; o[i] = x * __builtin_amdgcn_rcpf(1.f + __expf(-x)) * vl[i]; }
;                     u32x2 w; w.x = cvt_pk_bf16(o[0], o[1]); w.y = cvt_pk_bf16(o[2], o[3]);
;                     *(u32x2*)(O + (size_t)row * DFF + ch) = w;
.LBB0_495:
	s_or_b64 exec, exec, s[16:17]
	v_readlane_b32 s16, v255, 5
	v_readlane_b32 s17, v255, 6
	s_nop 1
	v_cndmask_b32_e64 v150, 0, 1, s[16:17]
	v_cmp_ne_u32_e64 s[16:17], 1, v150
	s_mov_b64 s[18:19], exec
	v_readlane_b32 s28, v255, 46
	v_readlane_b32 s29, v255, 47
	s_and_b64 s[28:29], s[18:19], s[28:29]
	s_mov_b64 exec, s[28:29]
.LBB0_500:
	ds_read_b128 v[150:153], v219 offset:1024
	s_waitcnt lgkmcnt(0)
	v_mov_b32_e32 v177, v152
	v_mov_b32_e32 v179, v150
.LBB0_501:
	s_or_b64 exec, exec, s[18:19]
	v_mov_b32_e32 v180, v60
	v_mov_b32_e32 v181, v138
	v_mov_b32_e32 v178, v134
	v_pk_mul_f32 v[178:179], v[180:181], v[178:179]
	v_mov_b32_e32 v176, v136
	s_waitcnt lgkmcnt(0)
	v_fma_f32 v146, v130, v146, v178
	v_add_f32_e32 v146, v146, v179
	v_add_f32_e32 v146, v142, v146
	v_mul_f32_e32 v150, 0xbfb8aa3b, v146
	v_exp_f32_e32 v150, v150
	v_mov_b32_e32 v178, v61
	v_mov_b32_e32 v179, v139
	v_readlane_b32 s18, v255, 2
	v_add_f32_e32 v150, 1.0, v150
	v_rcp_f32_e32 v152, v150
	v_mov_b32_e32 v150, v135
	v_pk_mul_f32 v[150:151], v[178:179], v[150:151]
	s_add_i32 s18, s67, s18
	v_fma_f32 v147, v131, v147, v150
	v_add_f32_e32 v147, v147, v151
	v_add_f32_e32 v150, v143, v147
	v_mul_f32_e32 v147, 0xbfb8aa3b, v150
	v_exp_f32_e32 v147, v147
	v_mul_f32_e32 v146, v146, v152
	v_mul_f32_e32 v178, v56, v146
	v_mov_b32_e32 v152, v137
	v_add_f32_e32 v146, 1.0, v147
	v_rcp_f32_e32 v179, v146
	v_mov_b32_e32 v146, v62
	v_mov_b32_e32 v147, v140
	v_pk_mul_f32 v[146:147], v[146:147], v[176:177]
	v_add_u32_e32 v151, s18, v189
	v_fma_f32 v146, v132, v148, v146
	v_add_f32_e32 v146, v146, v147
	v_add_f32_e32 v148, v144, v146
	v_mul_f32_e32 v146, 0xbfb8aa3b, v148
	v_exp_f32_e32 v176, v146
	v_mov_b32_e32 v146, v63
	v_mov_b32_e32 v147, v141
	v_pk_mul_f32 v[146:147], v[146:147], v[152:153]
	s_movk_i32 s18, 0x1600
	v_fma_f32 v146, v133, v149, v146
	v_add_f32_e32 v146, v146, v147
	v_add_f32_e32 v146, v145, v146
	v_mul_f32_e32 v147, 0xbfb8aa3b, v146
	v_exp_f32_e32 v147, v147
	v_mul_f32_e32 v149, v150, v179
	v_add_f32_e32 v150, 1.0, v176
	v_rcp_f32_e32 v150, v150
	v_add_f32_e32 v147, 1.0, v147
	v_rcp_f32_e32 v147, v147
	v_mul_f32_e32 v149, v57, v149
	v_mul_f32_e32 v148, v148, v150
	v_mul_f32_e32 v148, v58, v148
	v_mul_f32_e32 v146, v146, v147
	v_mul_f32_e32 v147, v59, v146
	v_cvt_pk_bf16_f32 v146, v178, v149
	v_cvt_pk_bf16_f32 v147, v148, v147
	v_mov_b64_e32 v[148:149], s[86:87]
	v_mad_i64_i32 v[176:177], s[18:19], v151, s18, v[148:149]
	v_readlane_b32 s18, v255, 8
	v_readlane_b32 s19, v255, 9
	v_lshl_add_u64 v[148:149], v[166:167], 1, v[176:177]
	global_store_dwordx2 v[148:149], v[146:147], off
	v_cndmask_b32_e64 v150, 0, 1, s[18:19]
	v_mov_b32_dpp v146, v44 row_shr:1 row_mask:0xf bank_mask:0xf bound_ctrl:1
	v_mov_b32_dpp v181, v44 row_shl:1 row_mask:0xf bank_mask:0xf bound_ctrl:1
	v_mov_b32_dpp v147, v45 row_shr:1 row_mask:0xf bank_mask:0xf bound_ctrl:1
	v_mov_b32_dpp v151, v45 row_shl:1 row_mask:0xf bank_mask:0xf bound_ctrl:1
	v_mov_b32_dpp v148, v46 row_shr:1 row_mask:0xf bank_mask:0xf bound_ctrl:1
	v_mov_b32_dpp v179, v46 row_shl:1 row_mask:0xf bank_mask:0xf bound_ctrl:1
	v_mov_b32_dpp v149, v47 row_shr:1 row_mask:0xf bank_mask:0xf bound_ctrl:1
	v_mov_b32_dpp v153, v47 row_shl:1 row_mask:0xf bank_mask:0xf bound_ctrl:1
	v_cmp_ne_u32_e64 s[18:19], 1, v150
	s_mov_b64 s[28:29], exec
	v_readlane_b32 s34, v255, 44
	v_readlane_b32 s35, v255, 45
	s_and_b64 s[34:35], s[28:29], s[34:35]
	s_mov_b64 exec, s[34:35]
	v_readlane_b32 s34, v255, 39
	s_nop 1
	v_lshl_add_u32 v146, v186, 2, s34
	ds_read_b128 v[146:149], v146
.LBB0_508:
	s_or_b64 exec, exec, s[28:29]
	s_mov_b64 s[28:29], exec
	v_readlane_b32 s34, v255, 46
	v_readlane_b32 s35, v255, 47
	s_and_b64 s[34:35], s[28:29], s[34:35]
	s_mov_b64 exec, s[34:35]
.LBB0_513:
	ds_read_b128 v[150:153], v218 offset:1024
	s_waitcnt lgkmcnt(0)
	v_mov_b32_e32 v179, v152
	v_mov_b32_e32 v181, v150
;     __device__ __forceinline__ void run_glu(const f32x4 (&acc)[2][2][4][2], const pg8::Unit& u, int wr, int wc, int fr, int fq) const {
;     ...
;         for (int bj = 0; bj < 2; ++bj) {
;             int col = u.pn * 256 + bj * 128 + wc * 32 + 8 * fq; asm volatile("" : "+v"(col)); const int ch = (col >> 3) * 4;
;             const f32x4 c0 = *(const f32x4*)(f0 + ch), c1 = *(const f32x4*)(f0 + DFF + ch), c2 = *(const f32x4*)(f0 + 2 * DFF + ch), cb = *(const f32x4*)(f1 + ch);
; #pragma unroll
;             for (int ai = 0; ai < 2; ++ai)
; #pragma unroll
;                 for (int m = 0; m < 4; ++m) { const int g = ai * 8 + wr * 4 + m;
;                     const int row = u.pm * 256 + g * 16 + fro;
;                     const f32x4 gt = acc[ai][bj][m][0], vl = acc[ai][bj][m][1];
;                     f32x4 gp, gn;
; #pragma unroll
;                     for (int i = 0; i < 4; ++i) { gp[i] = __int_as_float(__builtin_amdgcn_update_dpp(0, __float_as_int(gt[i]), 0x111, 0xF, 0xF, true));
;                                                   gn[i] = __int_as_float(__builtin_amdgcn_update_dpp(0, __float_as_int(gt[i]), 0x101, 0xF, 0xF, true)); }
;                     if (fr == 0) {
;                         if (g > 0) gp = *(const LAS f32x4*)(B + ((g - 1) * 2 + 1) * 128 + lidx + bj * 16);
;                         else if (!tfirst) { const u32x2 w = *(const u32x2*)(VFp + (size_t)(2 * (u.pm - 1)) * (2 * DFF) + col); gp = (f32x4){bflo(w.x), bfhi(w.x), bflo(w.y), bfhi(w.y)}; }
;                         else gp = (f32x4){0.f, 0.f, 0.f, 0.f};
;                     }
;                     if (fr == 15) {
;                         if (g < 15) gn = *(const LAS f32x4*)(B + ((g + 1) * 2 + 0) * 128 + lidx + bj * 16);
;                         else if (!tlast) { const u32x2 w = *(const u32x2*)(VFp + (size_t)(2 * u.pm + 1) * (2 * DFF) + col); gn = (f32x4){bflo(w.x), bfhi(w.x), bflo(w.y), bfhi(w.y)}; }
;                         else gn = (f32x4){0.f, 0.f, 0.f, 0.f};
;                     }
;                     float o[4];
; #pragma unroll
;                     for (int i = 0; i < 4; ++i) { const float x = gp[i] * c0[i] + gt[i] * c1[i] + gn[i] * c2[i] + cb[i]; o[i] = x * __builtin_amdgcn_rcpf(1.f + __expf(-x)) * vl[i]; }
;                     u32x2 w; w.x = cvt_pk_bf16(o[0], o[1]); w.y = cvt_pk_bf16(o[2], o[3]);
;                     *(u32x2*)(O + (size_t)row * DFF + ch) = w;
.LBB0_514:
	s_or_b64 exec, exec, s[28:29]
	v_mov_b32_e32 v184, v44
	v_mov_b32_e32 v185, v138
	v_mov_b32_e32 v180, v134
	v_pk_mul_f32 v[180:181], v[184:185], v[180:181]
	v_mov_b32_e32 v178, v136
	s_waitcnt lgkmcnt(0)
	v_fma_f32 v146, v130, v146, v180
	v_add_f32_e32 v146, v146, v181
	v_add_f32_e32 v146, v142, v146
	v_mul_f32_e32 v150, 0xbfb8aa3b, v146
	v_exp_f32_e32 v150, v150
	v_mov_b32_e32 v180, v45
	v_mov_b32_e32 v181, v139
	v_readlane_b32 s28, v255, 7
	v_add_f32_e32 v150, 1.0, v150
	v_rcp_f32_e32 v152, v150
	v_mov_b32_e32 v150, v135
	v_pk_mul_f32 v[150:151], v[180:181], v[150:151]
	s_add_i32 s28, s67, s28
	v_fma_f32 v147, v131, v147, v150
	v_add_f32_e32 v147, v147, v151
	v_add_f32_e32 v150, v143, v147
	v_mul_f32_e32 v147, 0xbfb8aa3b, v150
	v_exp_f32_e32 v147, v147
	v_mul_f32_e32 v146, v146, v152
	v_mul_f32_e32 v180, v40, v146
	v_mov_b32_e32 v152, v137
	v_add_f32_e32 v146, 1.0, v147
	v_rcp_f32_e32 v181, v146
	v_mov_b32_e32 v146, v46
	v_mov_b32_e32 v147, v140
	v_pk_mul_f32 v[146:147], v[146:147], v[178:179]
	v_add_u32_e32 v151, s28, v189
	v_fma_f32 v146, v132, v148, v146
	v_add_f32_e32 v146, v146, v147
	v_add_f32_e32 v148, v144, v146
	v_mul_f32_e32 v146, 0xbfb8aa3b, v148
	v_exp_f32_e32 v178, v146
	v_mov_b32_e32 v146, v47
	v_mov_b32_e32 v147, v141
	v_pk_mul_f32 v[146:147], v[146:147], v[152:153]
	s_movk_i32 s28, 0x1600
	v_fma_f32 v146, v133, v149, v146
	v_add_f32_e32 v146, v146, v147
	v_add_f32_e32 v146, v145, v146
	v_mul_f32_e32 v147, 0xbfb8aa3b, v146
	v_exp_f32_e32 v147, v147
	v_mul_f32_e32 v149, v150, v181
	v_add_f32_e32 v150, 1.0, v178
	v_rcp_f32_e32 v150, v150
	v_add_f32_e32 v147, 1.0, v147
	v_rcp_f32_e32 v147, v147
	v_mul_f32_e32 v149, v41, v149
	v_mul_f32_e32 v148, v148, v150
	v_mul_f32_e32 v148, v42, v148
	v_mul_f32_e32 v146, v146, v147
	v_mul_f32_e32 v147, v43, v146
	v_cvt_pk_bf16_f32 v146, v180, v149
	v_cvt_pk_bf16_f32 v147, v148, v147
	v_mov_b64_e32 v[148:149], s[86:87]
	v_mad_i64_i32 v[178:179], s[28:29], v151, s28, v[148:149]
	v_lshl_add_u64 v[148:149], v[166:167], 1, v[178:179]
	global_store_dwordx2 v[148:149], v[146:147], off
	v_mov_b32_dpp v146, v28 row_shr:1 row_mask:0xf bank_mask:0xf bound_ctrl:1
	v_mov_b32_dpp v185, v28 row_shl:1 row_mask:0xf bank_mask:0xf bound_ctrl:1
	v_mov_b32_dpp v147, v29 row_shr:1 row_mask:0xf bank_mask:0xf bound_ctrl:1
	v_mov_b32_dpp v151, v29 row_shl:1 row_mask:0xf bank_mask:0xf bound_ctrl:1
	v_mov_b32_dpp v148, v30 row_shr:1 row_mask:0xf bank_mask:0xf bound_ctrl:1
	v_mov_b32_dpp v181, v30 row_shl:1 row_mask:0xf bank_mask:0xf bound_ctrl:1
	v_mov_b32_dpp v149, v31 row_shr:1 row_mask:0xf bank_mask:0xf bound_ctrl:1
	v_mov_b32_dpp v153, v31 row_shl:1 row_mask:0xf bank_mask:0xf bound_ctrl:1
	s_mov_b64 s[28:29], exec
	v_readlane_b32 s34, v255, 44
	v_readlane_b32 s35, v255, 45
	s_and_b64 s[34:35], s[28:29], s[34:35]
	s_mov_b64 exec, s[34:35]
	v_readlane_b32 s34, v255, 41
	s_nop 1
	v_lshl_add_u32 v146, v186, 2, s34
	ds_read_b128 v[146:149], v146
.LBB0_521:
	s_or_b64 exec, exec, s[28:29]
	s_mov_b64 s[28:29], exec
	v_readlane_b32 s34, v255, 46
	v_readlane_b32 s35, v255, 47
	s_and_b64 s[34:35], s[28:29], s[34:35]
	s_mov_b64 exec, s[34:35]
.LBB0_526:
	ds_read_b128 v[150:153], v217 offset:1024
	s_waitcnt lgkmcnt(0)
	v_mov_b32_e32 v181, v152
	v_mov_b32_e32 v185, v150
.LBB0_527:
	s_or_b64 exec, exec, s[28:29]
	v_mov_b32_e32 v190, v28
	v_mov_b32_e32 v191, v138
	v_mov_b32_e32 v184, v134
	v_pk_mul_f32 v[184:185], v[190:191], v[184:185]
	v_mov_b32_e32 v180, v136
	s_waitcnt lgkmcnt(0)
	v_fma_f32 v146, v130, v146, v184
	v_add_f32_e32 v146, v146, v185
	v_add_f32_e32 v146, v142, v146
	v_mul_f32_e32 v150, 0xbfb8aa3b, v146
	v_exp_f32_e32 v150, v150
	v_mov_b32_e32 v184, v29
	v_mov_b32_e32 v185, v139
	v_readlane_b32 s28, v255, 10
	v_add_f32_e32 v150, 1.0, v150
	v_rcp_f32_e32 v152, v150
	v_mov_b32_e32 v150, v135
	v_pk_mul_f32 v[150:151], v[184:185], v[150:151]
	s_add_i32 s28, s67, s28
	v_fma_f32 v147, v131, v147, v150
	v_add_f32_e32 v147, v147, v151
	v_add_f32_e32 v150, v143, v147
	v_mul_f32_e32 v147, 0xbfb8aa3b, v150
	v_exp_f32_e32 v147, v147
	v_mul_f32_e32 v146, v146, v152
	v_mul_f32_e32 v184, v24, v146
	v_mov_b32_e32 v152, v137
	v_add_f32_e32 v146, 1.0, v147
	v_rcp_f32_e32 v185, v146
	v_mov_b32_e32 v146, v30
	v_mov_b32_e32 v147, v140
	v_pk_mul_f32 v[146:147], v[146:147], v[180:181]
	v_add_u32_e32 v151, s28, v189
	v_fma_f32 v146, v132, v148, v146
	v_add_f32_e32 v146, v146, v147
	v_add_f32_e32 v148, v144, v146
	v_mul_f32_e32 v146, 0xbfb8aa3b, v148
	v_exp_f32_e32 v180, v146
	v_mov_b32_e32 v146, v31
	v_mov_b32_e32 v147, v141
	v_pk_mul_f32 v[146:147], v[146:147], v[152:153]
	s_movk_i32 s28, 0x1600
	v_fma_f32 v146, v133, v149, v146
	v_add_f32_e32 v146, v146, v147
	v_add_f32_e32 v146, v145, v146
	v_mul_f32_e32 v147, 0xbfb8aa3b, v146
	v_exp_f32_e32 v147, v147
	v_mul_f32_e32 v149, v150, v185
	v_add_f32_e32 v150, 1.0, v180
	v_rcp_f32_e32 v150, v150
	v_add_f32_e32 v147, 1.0, v147
	v_rcp_f32_e32 v147, v147
	v_mul_f32_e32 v149, v25, v149
	v_mul_f32_e32 v148, v148, v150
	v_mul_f32_e32 v148, v26, v148
	v_mul_f32_e32 v146, v146, v147
	v_mul_f32_e32 v147, v27, v146
	v_cvt_pk_bf16_f32 v146, v184, v149
	v_cvt_pk_bf16_f32 v147, v148, v147
	v_mov_b64_e32 v[148:149], s[86:87]
	v_mad_i64_i32 v[180:181], s[28:29], v151, s28, v[148:149]
	v_lshl_add_u64 v[148:149], v[166:167], 1, v[180:181]
	global_store_dwordx2 v[148:149], v[146:147], off
	v_mov_b32_dpp v146, v12 row_shr:1 row_mask:0xf bank_mask:0xf bound_ctrl:1
	v_mov_b32_dpp v187, v12 row_shl:1 row_mask:0xf bank_mask:0xf bound_ctrl:1
	v_mov_b32_dpp v147, v13 row_shr:1 row_mask:0xf bank_mask:0xf bound_ctrl:1
	v_mov_b32_dpp v151, v13 row_shl:1 row_mask:0xf bank_mask:0xf bound_ctrl:1
	v_mov_b32_dpp v148, v14 row_shr:1 row_mask:0xf bank_mask:0xf bound_ctrl:1
	v_mov_b32_dpp v185, v14 row_shl:1 row_mask:0xf bank_mask:0xf bound_ctrl:1
	v_mov_b32_dpp v149, v15 row_shr:1 row_mask:0xf bank_mask:0xf bound_ctrl:1
	v_mov_b32_dpp v153, v15 row_shl:1 row_mask:0xf bank_mask:0xf bound_ctrl:1
	s_mov_b64 s[28:29], exec
	v_readlane_b32 s34, v255, 44
	v_readlane_b32 s35, v255, 45
	s_and_b64 s[34:35], s[28:29], s[34:35]
	s_mov_b64 exec, s[34:35]
	v_readlane_b32 s34, v255, 43
	s_nop 1
	v_lshl_add_u32 v146, v186, 2, s34
	ds_read_b128 v[146:149], v146

;     __device__ __forceinline__ void run_glu(const f32x4 (&acc)[2][2][4][2], const pg8::Unit& u, int wr, int wc, int fr, int fq) const {
;     ...
;         for (int bj = 0; bj < 2; ++bj) {
;             int col = u.pn * 256 + bj * 128 + wc * 32 + 8 * fq; asm volatile("" : "+v"(col)); const int ch = (col >> 3) * 4;
;             const f32x4 c0 = *(const f32x4*)(f0 + ch), c1 = *(const f32x4*)(f0 + DFF + ch), c2 = *(const f32x4*)(f0 + 2 * DFF + ch), cb = *(const f32x4*)(f1 + ch);
; #pragma unroll
;             for (int ai = 0; ai < 2; ++ai)
; #pragma unroll
;                 for (int m = 0; m < 4; ++m) { const int g = ai * 8 + wr * 4 + m;
;                     const int row = u.pm * 256 + g * 16 + fro;
;                     const f32x4 gt = acc[ai][bj][m][0], vl = acc[ai][bj][m][1];
;                     f32x4 gp, gn;
; #pragma unroll
;                     for (int i = 0; i < 4; ++i) { gp[i] = __int_as_float(__builtin_amdgcn_update_dpp(0, __float_as_int(gt[i]), 0x111, 0xF, 0xF, true));
;                                                   gn[i] = __int_as_float(__builtin_amdgcn_update_dpp(0, __float_as_int(gt[i]), 0x101, 0xF, 0xF, true)); }
;                     if (fr == 0) {
;                         if (g > 0) gp = *(const LAS f32x4*)(B + ((g - 1) * 2 + 1) * 128 + lidx + bj * 16);
;                         else if (!tfirst) { const u32x2 w = *(const u32x2*)(VFp + (size_t)(2 * (u.pm - 1)) * (2 * DFF) + col); gp = (f32x4){bflo(w.x), bfhi(w.x), bflo(w.y), bfhi(w.y)}; }
;                         else gp = (f32x4){0.f, 0.f, 0.f, 0.f};
;                     }
;                     if (fr == 15) {
;                         if (g < 15) gn = *(const LAS f32x4*)(B + ((g + 1) * 2 + 0) * 128 + lidx + bj * 16);
;                         else if (!tlast) { const u32x2 w = *(const u32x2*)(VFp + (size_t)(2 * u.pm + 1) * (2 * DFF) + col); gn = (f32x4){bflo(w.x), bfhi(w.x), bflo(w.y), bfhi(w.y)}; }
;                         else gn = (f32x4){0.f, 0.f, 0.f, 0.f};
;                     }
;                     float o[4];
; #pragma unroll
;                     for (int i = 0; i < 4; ++i) { const float x = gp[i] * c0[i] + gt[i] * c1[i] + gn[i] * c2[i] + cb[i]; o[i] = x * __builtin_amdgcn_rcpf(1.f + __expf(-x)) * vl[i]; }
;                     u32x2 w; w.x = cvt_pk_bf16(o[0], o[1]); w.y = cvt_pk_bf16(o[2], o[3]);
;                     *(u32x2*)(O + (size_t)row * DFF + ch) = w;
.LBB0_547:
	s_or_b64 exec, exec, s[34:35]
	s_mov_b64 s[34:35], exec
	v_readlane_b32 s54, v255, 46
	v_readlane_b32 s55, v255, 47
	s_and_b64 s[54:55], s[34:35], s[54:55]
	s_mov_b64 exec, s[54:55]
.LBB0_552:
	ds_read_b128 v[150:153], v188 offset:1088
	s_waitcnt lgkmcnt(0)
	v_mov_b32_e32 v187, v152
	v_mov_b32_e32 v189, v150
.LBB0_553:
	s_or_b64 exec, exec, s[34:35]
	v_mov_b32_e32 v190, v118
	s_waitcnt vmcnt(1)
	v_mov_b32_e32 v191, v138
	v_mov_b32_e32 v188, v134
	v_pk_mul_f32 v[188:189], v[190:191], v[188:189]
	v_mov_b32_e32 v186, v136
	s_waitcnt lgkmcnt(0)
	v_fma_f32 v146, v130, v146, v188
	v_add_f32_e32 v146, v146, v189
	s_waitcnt vmcnt(0)
	v_add_f32_e32 v146, v142, v146
	v_mul_f32_e32 v150, 0xbfb8aa3b, v146
	v_exp_f32_e32 v150, v150
	v_mov_b32_e32 v188, v119
	v_mov_b32_e32 v189, v139
	v_add_f32_e32 v150, 1.0, v150
	v_rcp_f32_e32 v152, v150
	v_mov_b32_e32 v150, v135
	v_pk_mul_f32 v[150:151], v[188:189], v[150:151]
	v_mul_f32_e32 v146, v146, v152
	v_fma_f32 v147, v131, v147, v150
	v_add_f32_e32 v147, v147, v151
	v_add_f32_e32 v150, v143, v147
	v_mul_f32_e32 v147, 0xbfb8aa3b, v150
	v_exp_f32_e32 v147, v147
	v_mul_f32_e32 v151, v114, v146
	v_mov_b32_e32 v152, v137
	v_add_f32_e32 v146, 1.0, v147
	v_rcp_f32_e32 v188, v146
	v_mov_b32_e32 v146, v120
	v_mov_b32_e32 v147, v140
	v_pk_mul_f32 v[146:147], v[146:147], v[186:187]
	v_mov_b32_dpp v187, v102 row_shl:1 row_mask:0xf bank_mask:0xf bound_ctrl:1
	v_fma_f32 v146, v132, v148, v146
	v_add_f32_e32 v146, v146, v147
	v_add_f32_e32 v148, v144, v146
	v_mul_f32_e32 v146, 0xbfb8aa3b, v148
	v_exp_f32_e32 v186, v146
	v_mov_b32_e32 v146, v121
	v_mov_b32_e32 v147, v141
	v_pk_mul_f32 v[146:147], v[146:147], v[152:153]
	v_mov_b32_dpp v153, v105 row_shl:1 row_mask:0xf bank_mask:0xf bound_ctrl:1
	v_fma_f32 v146, v133, v149, v146
	v_add_f32_e32 v146, v146, v147
	v_add_f32_e32 v146, v145, v146
	v_mul_f32_e32 v147, 0xbfb8aa3b, v146
	v_exp_f32_e32 v147, v147
	v_mul_f32_e32 v149, v150, v188
	v_add_f32_e32 v150, 1.0, v186
	v_rcp_f32_e32 v150, v150
	v_add_f32_e32 v147, 1.0, v147
	v_rcp_f32_e32 v147, v147
	v_mul_f32_e32 v149, v115, v149
	v_mul_f32_e32 v148, v148, v150
	v_mul_f32_e32 v148, v116, v148
	v_mul_f32_e32 v146, v146, v147
	v_mul_f32_e32 v147, v117, v146
	v_cvt_pk_bf16_f32 v146, v151, v149
	v_cvt_pk_bf16_f32 v147, v148, v147
	v_lshl_add_u64 v[148:149], v[166:167], 1, v[168:169]
	global_store_dwordx2 v[148:149], v[146:147], off
	v_mov_b32_dpp v146, v102 row_shr:1 row_mask:0xf bank_mask:0xf bound_ctrl:1
	v_mov_b32_dpp v147, v103 row_shr:1 row_mask:0xf bank_mask:0xf bound_ctrl:1
	v_mov_b32_dpp v151, v103 row_shl:1 row_mask:0xf bank_mask:0xf bound_ctrl:1
	v_mov_b32_dpp v148, v104 row_shr:1 row_mask:0xf bank_mask:0xf bound_ctrl:1
	v_mov_b32_dpp v169, v104 row_shl:1 row_mask:0xf bank_mask:0xf bound_ctrl:1
	v_mov_b32_dpp v149, v105 row_shr:1 row_mask:0xf bank_mask:0xf bound_ctrl:1
	s_mov_b64 s[34:35], exec
	v_readlane_b32 s54, v255, 44
	v_readlane_b32 s55, v255, 45
	s_and_b64 s[54:55], s[34:35], s[54:55]
	s_mov_b64 exec, s[54:55]
	v_add_u32_e32 v146, 0xfffffe40, v222
	ds_read_b128 v[146:149], v146
.LBB0_560:
	s_or_b64 exec, exec, s[34:35]
	s_mov_b64 s[34:35], exec
	v_readlane_b32 s54, v255, 46
	v_readlane_b32 s55, v255, 47
	s_and_b64 s[54:55], s[34:35], s[54:55]
	s_mov_b64 exec, s[54:55]
.LBB0_565:
	ds_read_b128 v[150:153], v222 offset:1088
	s_waitcnt lgkmcnt(0)
	v_mov_b32_e32 v169, v152
	v_mov_b32_e32 v187, v150
.LBB0_566:
	s_or_b64 exec, exec, s[34:35]
	v_mov_b32_e32 v188, v102
	v_mov_b32_e32 v189, v138
	v_mov_b32_e32 v186, v134
	v_pk_mul_f32 v[186:187], v[188:189], v[186:187]
	v_mov_b32_e32 v168, v136
	s_waitcnt lgkmcnt(0)
	v_fma_f32 v146, v130, v146, v186
	v_add_f32_e32 v146, v146, v187
	v_add_f32_e32 v146, v142, v146
	v_mul_f32_e32 v150, 0xbfb8aa3b, v146
	v_exp_f32_e32 v150, v150
	v_mov_b32_e32 v186, v103
	v_mov_b32_e32 v187, v139
	v_add_f32_e32 v150, 1.0, v150
	v_rcp_f32_e32 v152, v150
	v_mov_b32_e32 v150, v135
	v_pk_mul_f32 v[150:151], v[186:187], v[150:151]
	v_mul_f32_e32 v146, v146, v152
	v_fma_f32 v147, v131, v147, v150
	v_add_f32_e32 v147, v147, v151
	v_add_f32_e32 v150, v143, v147
	v_mul_f32_e32 v147, 0xbfb8aa3b, v150
	v_exp_f32_e32 v147, v147
	v_mul_f32_e32 v151, v98, v146
	v_mov_b32_e32 v152, v137
	v_add_f32_e32 v146, 1.0, v147
	v_rcp_f32_e32 v186, v146
	v_mov_b32_e32 v146, v104
	v_mov_b32_e32 v147, v140
	v_pk_mul_f32 v[146:147], v[146:147], v[168:169]
	v_mov_b32_dpp v169, v86 row_shl:1 row_mask:0xf bank_mask:0xf bound_ctrl:1
	v_fma_f32 v146, v132, v148, v146
	v_add_f32_e32 v146, v146, v147
	v_add_f32_e32 v148, v144, v146
	v_mul_f32_e32 v146, 0xbfb8aa3b, v148
	v_exp_f32_e32 v168, v146
	v_mov_b32_e32 v146, v105
	v_mov_b32_e32 v147, v141
	v_pk_mul_f32 v[146:147], v[146:147], v[152:153]
	v_mov_b32_dpp v153, v87 row_shl:1 row_mask:0xf bank_mask:0xf bound_ctrl:1
	v_fma_f32 v146, v133, v149, v146
	v_add_f32_e32 v146, v146, v147
	v_add_f32_e32 v146, v145, v146
	v_mul_f32_e32 v147, 0xbfb8aa3b, v146
	v_exp_f32_e32 v147, v147
	v_mul_f32_e32 v149, v150, v186
	v_add_f32_e32 v150, 1.0, v168
	v_rcp_f32_e32 v150, v150
	v_add_f32_e32 v147, 1.0, v147
	v_rcp_f32_e32 v147, v147
	v_mul_f32_e32 v149, v99, v149
	v_mul_f32_e32 v148, v148, v150
	v_mul_f32_e32 v148, v100, v148
	v_mul_f32_e32 v146, v146, v147
	v_mul_f32_e32 v147, v101, v146
	v_cvt_pk_bf16_f32 v146, v151, v149
	v_cvt_pk_bf16_f32 v147, v148, v147
	v_lshl_add_u64 v[148:149], v[166:167], 1, v[170:171]
	global_store_dwordx2 v[148:149], v[146:147], off
	v_mov_b32_dpp v146, v84 row_shr:1 row_mask:0xf bank_mask:0xf bound_ctrl:1
	v_mov_b32_dpp v171, v84 row_shl:1 row_mask:0xf bank_mask:0xf bound_ctrl:1
	v_mov_b32_dpp v147, v85 row_shr:1 row_mask:0xf bank_mask:0xf bound_ctrl:1
	v_mov_b32_dpp v151, v85 row_shl:1 row_mask:0xf bank_mask:0xf bound_ctrl:1
	v_mov_b32_dpp v148, v86 row_shr:1 row_mask:0xf bank_mask:0xf bound_ctrl:1
	v_mov_b32_dpp v149, v87 row_shr:1 row_mask:0xf bank_mask:0xf bound_ctrl:1
	s_mov_b64 s[20:21], exec
	v_readlane_b32 s34, v255, 44
	v_readlane_b32 s35, v255, 45
	s_and_b64 s[34:35], s[20:21], s[34:35]
	s_mov_b64 exec, s[34:35]
	v_add_u32_e32 v146, 0xfffffe40, v221
	ds_read_b128 v[146:149], v146
;     __device__ __forceinline__ void run_glu(const f32x4 (&acc)[2][2][4][2], const pg8::Unit& u, int wr, int wc, int fr, int fq) const {
;     ...
;         for (int bj = 0; bj < 2; ++bj) {
;             int col = u.pn * 256 + bj * 128 + wc * 32 + 8 * fq; asm volatile("" : "+v"(col)); const int ch = (col >> 3) * 4;
;             const f32x4 c0 = *(const f32x4*)(f0 + ch), c1 = *(const f32x4*)(f0 + DFF + ch), c2 = *(const f32x4*)(f0 + 2 * DFF + ch), cb = *(const f32x4*)(f1 + ch);
; #pragma unroll
;             for (int ai = 0; ai < 2; ++ai)
; #pragma unroll
;                 for (int m = 0; m < 4; ++m) { const int g = ai * 8 + wr * 4 + m;
;                     const int row = u.pm * 256 + g * 16 + fro;
;                     const f32x4 gt = acc[ai][bj][m][0], vl = acc[ai][bj][m][1];
;                     f32x4 gp, gn;
; #pragma unroll
;                     for (int i = 0; i < 4; ++i) { gp[i] = __int_as_float(__builtin_amdgcn_update_dpp(0, __float_as_int(gt[i]), 0x111, 0xF, 0xF, true));
;                                                   gn[i] = __int_as_float(__builtin_amdgcn_update_dpp(0, __float_as_int(gt[i]), 0x101, 0xF, 0xF, true)); }
;                     if (fr == 0) {
;                         if (g > 0) gp = *(const LAS f32x4*)(B + ((g - 1) * 2 + 1) * 128 + lidx + bj * 16);
;                         else if (!tfirst) { const u32x2 w = *(const u32x2*)(VFp + (size_t)(2 * (u.pm - 1)) * (2 * DFF) + col); gp = (f32x4){bflo(w.x), bfhi(w.x), bflo(w.y), bfhi(w.y)}; }
;                         else gp = (f32x4){0.f, 0.f, 0.f, 0.f};
;                     }
;                     if (fr == 15) {
;                         if (g < 15) gn = *(const LAS f32x4*)(B + ((g + 1) * 2 + 0) * 128 + lidx + bj * 16);
;                         else if (!tlast) { const u32x2 w = *(const u32x2*)(VFp + (size_t)(2 * u.pm + 1) * (2 * DFF) + col); gn = (f32x4){bflo(w.x), bfhi(w.x), bflo(w.y), bfhi(w.y)}; }
;                         else gn = (f32x4){0.f, 0.f, 0.f, 0.f};
;                     }
;                     float o[4];
; #pragma unroll
;                     for (int i = 0; i < 4; ++i) { const float x = gp[i] * c0[i] + gt[i] * c1[i] + gn[i] * c2[i] + cb[i]; o[i] = x * __builtin_amdgcn_rcpf(1.f + __expf(-x)) * vl[i]; }
;                     u32x2 w; w.x = cvt_pk_bf16(o[0], o[1]); w.y = cvt_pk_bf16(o[2], o[3]);
;                     *(u32x2*)(O + (size_t)row * DFF + ch) = w;
.LBB0_573:
	s_or_b64 exec, exec, s[20:21]
	s_mov_b64 s[20:21], exec
	v_readlane_b32 s34, v255, 46
	v_readlane_b32 s35, v255, 47
	s_and_b64 s[34:35], s[20:21], s[34:35]
	s_mov_b64 exec, s[34:35]
.LBB0_578:
	ds_read_b128 v[150:153], v221 offset:1088
	s_waitcnt lgkmcnt(0)
	v_mov_b32_e32 v169, v152
	v_mov_b32_e32 v171, v150
.LBB0_579:
	s_or_b64 exec, exec, s[20:21]
	v_mov_b32_e32 v186, v84
	v_mov_b32_e32 v187, v138
	v_mov_b32_e32 v170, v134
	v_pk_mul_f32 v[170:171], v[186:187], v[170:171]
	v_mov_b32_e32 v168, v136
	s_waitcnt lgkmcnt(0)
	v_fma_f32 v146, v130, v146, v170
	v_add_f32_e32 v146, v146, v171
	v_add_f32_e32 v146, v142, v146
	v_mul_f32_e32 v150, 0xbfb8aa3b, v146
	v_exp_f32_e32 v150, v150
	v_mov_b32_e32 v170, v85
	v_mov_b32_e32 v171, v139
	v_add_f32_e32 v150, 1.0, v150
	v_rcp_f32_e32 v152, v150
	v_mov_b32_e32 v150, v135
	v_pk_mul_f32 v[150:151], v[170:171], v[150:151]
	v_mov_b32_dpp v171, v68 row_shl:1 row_mask:0xf bank_mask:0xf bound_ctrl:1
	v_fma_f32 v147, v131, v147, v150
	v_add_f32_e32 v147, v147, v151
	v_add_f32_e32 v150, v143, v147
	v_mul_f32_e32 v147, 0xbfb8aa3b, v150
	v_exp_f32_e32 v147, v147
	v_mul_f32_e32 v146, v146, v152
	v_mul_f32_e32 v151, v80, v146
	v_mov_b32_e32 v152, v137
	v_add_f32_e32 v146, 1.0, v147
	v_rcp_f32_e32 v170, v146
	v_mov_b32_e32 v146, v86
	v_mov_b32_e32 v147, v140
	v_pk_mul_f32 v[146:147], v[146:147], v[168:169]
	v_mov_b32_dpp v169, v70 row_shl:1 row_mask:0xf bank_mask:0xf bound_ctrl:1
	v_fma_f32 v146, v132, v148, v146
	v_add_f32_e32 v146, v146, v147
	v_add_f32_e32 v148, v144, v146
	v_mul_f32_e32 v146, 0xbfb8aa3b, v148
	v_exp_f32_e32 v168, v146
	v_mov_b32_e32 v146, v87
	v_mov_b32_e32 v147, v141
	v_pk_mul_f32 v[146:147], v[146:147], v[152:153]
	v_mov_b32_dpp v153, v71 row_shl:1 row_mask:0xf bank_mask:0xf bound_ctrl:1
	v_fma_f32 v146, v133, v149, v146
	v_add_f32_e32 v146, v146, v147
	v_add_f32_e32 v146, v145, v146
	v_mul_f32_e32 v147, 0xbfb8aa3b, v146
	v_exp_f32_e32 v147, v147
	v_mul_f32_e32 v149, v150, v170
	v_add_f32_e32 v150, 1.0, v168
	v_rcp_f32_e32 v150, v150
	v_add_f32_e32 v147, 1.0, v147
	v_rcp_f32_e32 v147, v147
	v_mul_f32_e32 v149, v81, v149
	v_mul_f32_e32 v148, v148, v150
	v_mul_f32_e32 v148, v82, v148
	v_mul_f32_e32 v146, v146, v147
	v_mul_f32_e32 v147, v83, v146
	v_cvt_pk_bf16_f32 v146, v151, v149
	v_cvt_pk_bf16_f32 v147, v148, v147
	v_lshl_add_u64 v[148:149], v[166:167], 1, v[172:173]
	global_store_dwordx2 v[148:149], v[146:147], off
	v_mov_b32_dpp v146, v68 row_shr:1 row_mask:0xf bank_mask:0xf bound_ctrl:1
	v_mov_b32_dpp v147, v69 row_shr:1 row_mask:0xf bank_mask:0xf bound_ctrl:1
	v_mov_b32_dpp v151, v69 row_shl:1 row_mask:0xf bank_mask:0xf bound_ctrl:1
	v_mov_b32_dpp v148, v70 row_shr:1 row_mask:0xf bank_mask:0xf bound_ctrl:1
	v_mov_b32_dpp v149, v71 row_shr:1 row_mask:0xf bank_mask:0xf bound_ctrl:1
	s_mov_b64 s[20:21], exec
	v_readlane_b32 s22, v255, 44
	v_readlane_b32 s23, v255, 45
	s_and_b64 s[22:23], s[20:21], s[22:23]
	s_mov_b64 exec, s[22:23]
	v_add_u32_e32 v146, 0xfffffe40, v220
	ds_read_b128 v[146:149], v146
.LBB0_586:
	s_or_b64 exec, exec, s[20:21]
	s_mov_b64 s[14:15], exec
	v_readlane_b32 s20, v255, 46
	v_readlane_b32 s21, v255, 47
	s_and_b64 s[20:21], s[14:15], s[20:21]
	s_mov_b64 exec, s[20:21]
.LBB0_591:
	ds_read_b128 v[150:153], v220 offset:1088
	s_waitcnt lgkmcnt(0)
	v_mov_b32_e32 v169, v152
	v_mov_b32_e32 v171, v150
.LBB0_592:
	s_or_b64 exec, exec, s[14:15]
	v_mov_b32_e32 v172, v68
	v_mov_b32_e32 v173, v138
	v_mov_b32_e32 v170, v134
	v_pk_mul_f32 v[170:171], v[172:173], v[170:171]
	v_mov_b32_e32 v168, v136
	s_waitcnt lgkmcnt(0)
	v_fma_f32 v146, v130, v146, v170
	v_add_f32_e32 v146, v146, v171
	v_add_f32_e32 v146, v142, v146
	v_mul_f32_e32 v150, 0xbfb8aa3b, v146
	v_exp_f32_e32 v150, v150
	v_mov_b32_e32 v170, v69
	v_mov_b32_e32 v171, v139
	v_add_f32_e32 v150, 1.0, v150
	v_rcp_f32_e32 v152, v150
	v_mov_b32_e32 v150, v135
	v_pk_mul_f32 v[150:151], v[170:171], v[150:151]
	v_mov_b32_dpp v171, v52 row_shl:1 row_mask:0xf bank_mask:0xf bound_ctrl:1
	v_fma_f32 v147, v131, v147, v150
	v_add_f32_e32 v147, v147, v151
	v_add_f32_e32 v150, v143, v147
	v_mul_f32_e32 v147, 0xbfb8aa3b, v150
	v_exp_f32_e32 v147, v147
	v_mul_f32_e32 v146, v146, v152
	v_mul_f32_e32 v151, v64, v146
	v_mov_b32_e32 v152, v137
	v_add_f32_e32 v146, 1.0, v147
	v_rcp_f32_e32 v170, v146
	v_mov_b32_e32 v146, v70
	v_mov_b32_e32 v147, v140
	v_pk_mul_f32 v[146:147], v[146:147], v[168:169]
	v_mov_b32_dpp v169, v54 row_shl:1 row_mask:0xf bank_mask:0xf bound_ctrl:1
	v_fma_f32 v146, v132, v148, v146
	v_add_f32_e32 v146, v146, v147
	v_add_f32_e32 v148, v144, v146
	v_mul_f32_e32 v146, 0xbfb8aa3b, v148
	v_exp_f32_e32 v168, v146
	v_mov_b32_e32 v146, v71
	v_mov_b32_e32 v147, v141
	v_pk_mul_f32 v[146:147], v[146:147], v[152:153]
	v_mov_b32_dpp v153, v55 row_shl:1 row_mask:0xf bank_mask:0xf bound_ctrl:1
	v_fma_f32 v146, v133, v149, v146
	v_add_f32_e32 v146, v146, v147
	v_add_f32_e32 v146, v145, v146
	v_mul_f32_e32 v147, 0xbfb8aa3b, v146
	v_exp_f32_e32 v147, v147
	v_mul_f32_e32 v149, v150, v170
	v_add_f32_e32 v150, 1.0, v168
	v_rcp_f32_e32 v150, v150
	v_add_f32_e32 v147, 1.0, v147
	v_rcp_f32_e32 v147, v147
	v_mul_f32_e32 v149, v65, v149
	v_mul_f32_e32 v148, v148, v150
	v_mul_f32_e32 v148, v66, v148
	v_mul_f32_e32 v146, v146, v147
	v_mul_f32_e32 v147, v67, v146
	v_cvt_pk_bf16_f32 v146, v151, v149
	v_cvt_pk_bf16_f32 v147, v148, v147
	v_lshl_add_u64 v[148:149], v[166:167], 1, v[174:175]
	global_store_dwordx2 v[148:149], v[146:147], off
	v_mov_b32_dpp v146, v52 row_shr:1 row_mask:0xf bank_mask:0xf bound_ctrl:1
	v_mov_b32_dpp v147, v53 row_shr:1 row_mask:0xf bank_mask:0xf bound_ctrl:1
	v_mov_b32_dpp v151, v53 row_shl:1 row_mask:0xf bank_mask:0xf bound_ctrl:1
	v_mov_b32_dpp v148, v54 row_shr:1 row_mask:0xf bank_mask:0xf bound_ctrl:1
	v_mov_b32_dpp v149, v55 row_shr:1 row_mask:0xf bank_mask:0xf bound_ctrl:1
	s_mov_b64 s[14:15], exec
	v_readlane_b32 s20, v255, 44
	v_readlane_b32 s21, v255, 45
	s_and_b64 s[20:21], s[14:15], s[20:21]
	s_mov_b64 exec, s[20:21]
	v_add_u32_e32 v146, 0xfffffe40, v219
	ds_read_b128 v[146:149], v146
;     __device__ __forceinline__ void run_glu(const f32x4 (&acc)[2][2][4][2], const pg8::Unit& u, int wr, int wc, int fr, int fq) const {
;     ...
;         for (int bj = 0; bj < 2; ++bj) {
;             int col = u.pn * 256 + bj * 128 + wc * 32 + 8 * fq; asm volatile("" : "+v"(col)); const int ch = (col >> 3) * 4;
;             const f32x4 c0 = *(const f32x4*)(f0 + ch), c1 = *(const f32x4*)(f0 + DFF + ch), c2 = *(const f32x4*)(f0 + 2 * DFF + ch), cb = *(const f32x4*)(f1 + ch);
; #pragma unroll
;             for (int ai = 0; ai < 2; ++ai)
; #pragma unroll
;                 for (int m = 0; m < 4; ++m) { const int g = ai * 8 + wr * 4 + m;
;                     const int row = u.pm * 256 + g * 16 + fro;
;                     const f32x4 gt = acc[ai][bj][m][0], vl = acc[ai][bj][m][1];
;                     f32x4 gp, gn;
; #pragma unroll
;                     for (int i = 0; i < 4; ++i) { gp[i] = __int_as_float(__builtin_amdgcn_update_dpp(0, __float_as_int(gt[i]), 0x111, 0xF, 0xF, true));
;                                                   gn[i] = __int_as_float(__builtin_amdgcn_update_dpp(0, __float_as_int(gt[i]), 0x101, 0xF, 0xF, true)); }
;                     if (fr == 0) {
;                         if (g > 0) gp = *(const LAS f32x4*)(B + ((g - 1) * 2 + 1) * 128 + lidx + bj * 16);
;                         else if (!tfirst) { const u32x2 w = *(const u32x2*)(VFp + (size_t)(2 * (u.pm - 1)) * (2 * DFF) + col); gp = (f32x4){bflo(w.x), bfhi(w.x), bflo(w.y), bfhi(w.y)}; }
;                         else gp = (f32x4){0.f, 0.f, 0.f, 0.f};
;                     }
;                     if (fr == 15) {
;                         if (g < 15) gn = *(const LAS f32x4*)(B + ((g + 1) * 2 + 0) * 128 + lidx + bj * 16);
;                         else if (!tlast) { const u32x2 w = *(const u32x2*)(VFp + (size_t)(2 * u.pm + 1) * (2 * DFF) + col); gn = (f32x4){bflo(w.x), bfhi(w.x), bflo(w.y), bfhi(w.y)}; }
;                         else gn = (f32x4){0.f, 0.f, 0.f, 0.f};
;                     }
;                     float o[4];
; #pragma unroll
;                     for (int i = 0; i < 4; ++i) { const float x = gp[i] * c0[i] + gt[i] * c1[i] + gn[i] * c2[i] + cb[i]; o[i] = x * __builtin_amdgcn_rcpf(1.f + __expf(-x)) * vl[i]; }
;                     u32x2 w; w.x = cvt_pk_bf16(o[0], o[1]); w.y = cvt_pk_bf16(o[2], o[3]);
;                     *(u32x2*)(O + (size_t)row * DFF + ch) = w;
.LBB0_599:
	s_or_b64 exec, exec, s[14:15]
	s_mov_b64 s[14:15], exec
	v_readlane_b32 s20, v255, 46
	v_readlane_b32 s21, v255, 47
	s_and_b64 s[20:21], s[14:15], s[20:21]
	s_mov_b64 exec, s[20:21]
.LBB0_604:
	ds_read_b128 v[150:153], v219 offset:1088
	s_waitcnt lgkmcnt(0)
	v_mov_b32_e32 v169, v152
	v_mov_b32_e32 v171, v150
.LBB0_605:
	s_or_b64 exec, exec, s[14:15]
	v_mov_b32_e32 v172, v52
	v_mov_b32_e32 v173, v138
	v_mov_b32_e32 v170, v134
	v_pk_mul_f32 v[170:171], v[172:173], v[170:171]
	v_mov_b32_e32 v168, v136
	s_waitcnt lgkmcnt(0)
	v_fma_f32 v146, v130, v146, v170
	v_add_f32_e32 v146, v146, v171
	v_add_f32_e32 v146, v142, v146
	v_mul_f32_e32 v150, 0xbfb8aa3b, v146
	v_exp_f32_e32 v150, v150
	v_mov_b32_e32 v170, v53
	v_mov_b32_e32 v171, v139
	v_add_f32_e32 v150, 1.0, v150
	v_rcp_f32_e32 v152, v150
	v_mov_b32_e32 v150, v135
	v_pk_mul_f32 v[150:151], v[170:171], v[150:151]
	v_mov_b32_dpp v171, v36 row_shl:1 row_mask:0xf bank_mask:0xf bound_ctrl:1
	v_fma_f32 v147, v131, v147, v150
	v_add_f32_e32 v147, v147, v151
	v_add_f32_e32 v150, v143, v147
	v_mul_f32_e32 v147, 0xbfb8aa3b, v150
	v_exp_f32_e32 v147, v147
	v_mul_f32_e32 v146, v146, v152
	v_mul_f32_e32 v151, v48, v146
	v_mov_b32_e32 v152, v137
	v_add_f32_e32 v146, 1.0, v147
	v_rcp_f32_e32 v170, v146
	v_mov_b32_e32 v146, v54
	v_mov_b32_e32 v147, v140
	v_pk_mul_f32 v[146:147], v[146:147], v[168:169]
	v_mov_b32_dpp v169, v38 row_shl:1 row_mask:0xf bank_mask:0xf bound_ctrl:1
	v_fma_f32 v146, v132, v148, v146
	v_add_f32_e32 v146, v146, v147
	v_add_f32_e32 v148, v144, v146
	v_mul_f32_e32 v146, 0xbfb8aa3b, v148
	v_exp_f32_e32 v168, v146
	v_mov_b32_e32 v146, v55
	v_mov_b32_e32 v147, v141
	v_pk_mul_f32 v[146:147], v[146:147], v[152:153]
	v_mov_b32_dpp v153, v39 row_shl:1 row_mask:0xf bank_mask:0xf bound_ctrl:1
	v_fma_f32 v146, v133, v149, v146
	v_add_f32_e32 v146, v146, v147
	v_add_f32_e32 v146, v145, v146
	v_mul_f32_e32 v147, 0xbfb8aa3b, v146
	v_exp_f32_e32 v147, v147
	v_mul_f32_e32 v149, v150, v170
	v_add_f32_e32 v150, 1.0, v168
	v_rcp_f32_e32 v150, v150
	v_add_f32_e32 v147, 1.0, v147
	v_rcp_f32_e32 v147, v147
	v_mul_f32_e32 v149, v49, v149
	v_mul_f32_e32 v148, v148, v150
	v_mul_f32_e32 v148, v50, v148
	v_mul_f32_e32 v146, v146, v147
	v_mul_f32_e32 v147, v51, v146
	v_cvt_pk_bf16_f32 v146, v151, v149
	v_cvt_pk_bf16_f32 v147, v148, v147
	v_lshl_add_u64 v[148:149], v[166:167], 1, v[176:177]
	global_store_dwordx2 v[148:149], v[146:147], off
	v_mov_b32_dpp v146, v36 row_shr:1 row_mask:0xf bank_mask:0xf bound_ctrl:1
	v_mov_b32_dpp v147, v37 row_shr:1 row_mask:0xf bank_mask:0xf bound_ctrl:1
	v_mov_b32_dpp v151, v37 row_shl:1 row_mask:0xf bank_mask:0xf bound_ctrl:1
	v_mov_b32_dpp v148, v38 row_shr:1 row_mask:0xf bank_mask:0xf bound_ctrl:1
	v_mov_b32_dpp v149, v39 row_shr:1 row_mask:0xf bank_mask:0xf bound_ctrl:1
	s_mov_b64 s[14:15], exec
	v_readlane_b32 s20, v255, 44
	v_readlane_b32 s21, v255, 45
	s_and_b64 s[20:21], s[14:15], s[20:21]
	s_mov_b64 exec, s[20:21]
	v_add_u32_e32 v146, 0xfffffe40, v218
	ds_read_b128 v[146:149], v146
.LBB0_612:
	s_or_b64 exec, exec, s[14:15]
	s_mov_b64 s[14:15], exec
	v_readlane_b32 s20, v255, 46
	v_readlane_b32 s21, v255, 47
	s_and_b64 s[20:21], s[14:15], s[20:21]
	s_mov_b64 exec, s[20:21]
.LBB0_617:
	ds_read_b128 v[150:153], v218 offset:1088
	s_waitcnt lgkmcnt(0)
	v_mov_b32_e32 v169, v152
	v_mov_b32_e32 v171, v150
;     __device__ __forceinline__ void run_glu(const f32x4 (&acc)[2][2][4][2], const pg8::Unit& u, int wr, int wc, int fr, int fq) const {
;     ...
;         for (int bj = 0; bj < 2; ++bj) {
;             int col = u.pn * 256 + bj * 128 + wc * 32 + 8 * fq; asm volatile("" : "+v"(col)); const int ch = (col >> 3) * 4;
;             const f32x4 c0 = *(const f32x4*)(f0 + ch), c1 = *(const f32x4*)(f0 + DFF + ch), c2 = *(const f32x4*)(f0 + 2 * DFF + ch), cb = *(const f32x4*)(f1 + ch);
; #pragma unroll
;             for (int ai = 0; ai < 2; ++ai)
; #pragma unroll
;                 for (int m = 0; m < 4; ++m) { const int g = ai * 8 + wr * 4 + m;
;                     const int row = u.pm * 256 + g * 16 + fro;
;                     const f32x4 gt = acc[ai][bj][m][0], vl = acc[ai][bj][m][1];
;                     f32x4 gp, gn;
; #pragma unroll
;                     for (int i = 0; i < 4; ++i) { gp[i] = __int_as_float(__builtin_amdgcn_update_dpp(0, __float_as_int(gt[i]), 0x111, 0xF, 0xF, true));
;                                                   gn[i] = __int_as_float(__builtin_amdgcn_update_dpp(0, __float_as_int(gt[i]), 0x101, 0xF, 0xF, true)); }
;                     if (fr == 0) {
;                         if (g > 0) gp = *(const LAS f32x4*)(B + ((g - 1) * 2 + 1) * 128 + lidx + bj * 16);
;                         else if (!tfirst) { const u32x2 w = *(const u32x2*)(VFp + (size_t)(2 * (u.pm - 1)) * (2 * DFF) + col); gp = (f32x4){bflo(w.x), bfhi(w.x), bflo(w.y), bfhi(w.y)}; }
;                         else gp = (f32x4){0.f, 0.f, 0.f, 0.f};
;                     }
;                     if (fr == 15) {
;                         if (g < 15) gn = *(const LAS f32x4*)(B + ((g + 1) * 2 + 0) * 128 + lidx + bj * 16);
;                         else if (!tlast) { const u32x2 w = *(const u32x2*)(VFp + (size_t)(2 * u.pm + 1) * (2 * DFF) + col); gn = (f32x4){bflo(w.x), bfhi(w.x), bflo(w.y), bfhi(w.y)}; }
;                         else gn = (f32x4){0.f, 0.f, 0.f, 0.f};
;                     }
;                     float o[4];
; #pragma unroll
;                     for (int i = 0; i < 4; ++i) { const float x = gp[i] * c0[i] + gt[i] * c1[i] + gn[i] * c2[i] + cb[i]; o[i] = x * __builtin_amdgcn_rcpf(1.f + __expf(-x)) * vl[i]; }
;                     u32x2 w; w.x = cvt_pk_bf16(o[0], o[1]); w.y = cvt_pk_bf16(o[2], o[3]);
;                     *(u32x2*)(O + (size_t)row * DFF + ch) = w;
.LBB0_618:
	s_or_b64 exec, exec, s[14:15]
	v_mov_b32_e32 v172, v36
	v_mov_b32_e32 v173, v138
	v_mov_b32_e32 v170, v134
	v_pk_mul_f32 v[170:171], v[172:173], v[170:171]
	v_mov_b32_e32 v168, v136
	s_waitcnt lgkmcnt(0)
	v_fma_f32 v146, v130, v146, v170
	v_add_f32_e32 v146, v146, v171
	v_add_f32_e32 v146, v142, v146
	v_mul_f32_e32 v150, 0xbfb8aa3b, v146
	v_exp_f32_e32 v150, v150
	v_mov_b32_e32 v170, v37
	v_mov_b32_e32 v171, v139
	v_add_f32_e32 v150, 1.0, v150
	v_rcp_f32_e32 v152, v150
	v_mov_b32_e32 v150, v135
	v_pk_mul_f32 v[150:151], v[170:171], v[150:151]
	v_mov_b32_dpp v171, v20 row_shl:1 row_mask:0xf bank_mask:0xf bound_ctrl:1
	v_fma_f32 v147, v131, v147, v150
	v_add_f32_e32 v147, v147, v151
	v_add_f32_e32 v150, v143, v147
	v_mul_f32_e32 v147, 0xbfb8aa3b, v150
	v_exp_f32_e32 v147, v147
	v_mul_f32_e32 v146, v146, v152
	v_mul_f32_e32 v151, v32, v146
	v_mov_b32_e32 v152, v137
	v_add_f32_e32 v146, 1.0, v147
	v_rcp_f32_e32 v170, v146
	v_mov_b32_e32 v146, v38
	v_mov_b32_e32 v147, v140
	v_pk_mul_f32 v[146:147], v[146:147], v[168:169]
	v_mov_b32_dpp v169, v22 row_shl:1 row_mask:0xf bank_mask:0xf bound_ctrl:1
	v_fma_f32 v146, v132, v148, v146
	v_add_f32_e32 v146, v146, v147
	v_add_f32_e32 v148, v144, v146
	v_mul_f32_e32 v146, 0xbfb8aa3b, v148
	v_exp_f32_e32 v168, v146
	v_mov_b32_e32 v146, v39
	v_mov_b32_e32 v147, v141
	v_pk_mul_f32 v[146:147], v[146:147], v[152:153]
	v_mov_b32_dpp v153, v23 row_shl:1 row_mask:0xf bank_mask:0xf bound_ctrl:1
	v_fma_f32 v146, v133, v149, v146
	v_add_f32_e32 v146, v146, v147
	v_add_f32_e32 v146, v145, v146
	v_mul_f32_e32 v147, 0xbfb8aa3b, v146
	v_exp_f32_e32 v147, v147
	v_mul_f32_e32 v149, v150, v170
	v_add_f32_e32 v150, 1.0, v168
	v_rcp_f32_e32 v150, v150
	v_add_f32_e32 v147, 1.0, v147
	v_rcp_f32_e32 v147, v147
	v_mul_f32_e32 v149, v33, v149
	v_mul_f32_e32 v148, v148, v150
	v_mul_f32_e32 v148, v34, v148
	v_mul_f32_e32 v146, v146, v147
	v_mul_f32_e32 v147, v35, v146
	v_cvt_pk_bf16_f32 v146, v151, v149
	v_cvt_pk_bf16_f32 v147, v148, v147
	v_lshl_add_u64 v[148:149], v[166:167], 1, v[178:179]
	global_store_dwordx2 v[148:149], v[146:147], off
	v_mov_b32_dpp v146, v20 row_shr:1 row_mask:0xf bank_mask:0xf bound_ctrl:1
	v_mov_b32_dpp v147, v21 row_shr:1 row_mask:0xf bank_mask:0xf bound_ctrl:1
	v_mov_b32_dpp v151, v21 row_shl:1 row_mask:0xf bank_mask:0xf bound_ctrl:1
	v_mov_b32_dpp v148, v22 row_shr:1 row_mask:0xf bank_mask:0xf bound_ctrl:1
	v_mov_b32_dpp v149, v23 row_shr:1 row_mask:0xf bank_mask:0xf bound_ctrl:1
	s_mov_b64 s[14:15], exec
	v_readlane_b32 s20, v255, 44
	v_readlane_b32 s21, v255, 45
	s_and_b64 s[20:21], s[14:15], s[20:21]
	s_mov_b64 exec, s[20:21]
	v_add_u32_e32 v146, 0xfffffe40, v217
	ds_read_b128 v[146:149], v146
.LBB0_625:
	s_or_b64 exec, exec, s[14:15]
	s_mov_b64 s[14:15], exec
	v_readlane_b32 s20, v255, 46
	v_readlane_b32 s21, v255, 47
	s_and_b64 s[20:21], s[14:15], s[20:21]
	s_mov_b64 exec, s[20:21]
.LBB0_630:
	ds_read_b128 v[150:153], v217 offset:1088
	s_waitcnt lgkmcnt(0)
	v_mov_b32_e32 v169, v152
	v_mov_b32_e32 v171, v150
.LBB0_631:
	s_or_b64 exec, exec, s[14:15]
	v_mov_b32_e32 v172, v20
	v_mov_b32_e32 v173, v138
	v_mov_b32_e32 v170, v134
	v_pk_mul_f32 v[170:171], v[172:173], v[170:171]
	v_mov_b32_e32 v168, v136
	s_waitcnt lgkmcnt(0)
	v_fma_f32 v146, v130, v146, v170
	v_add_f32_e32 v146, v146, v171
	v_add_f32_e32 v146, v142, v146
	v_mul_f32_e32 v150, 0xbfb8aa3b, v146
	v_exp_f32_e32 v150, v150
	v_mov_b32_e32 v170, v21
	v_mov_b32_e32 v171, v139
	v_add_f32_e32 v150, 1.0, v150
	v_rcp_f32_e32 v152, v150
	v_mov_b32_e32 v150, v135
	v_pk_mul_f32 v[150:151], v[170:171], v[150:151]
	v_mov_b32_dpp v171, v4 row_shl:1 row_mask:0xf bank_mask:0xf bound_ctrl:1
	v_fma_f32 v147, v131, v147, v150
	v_add_f32_e32 v147, v147, v151
	v_add_f32_e32 v150, v143, v147
	v_mul_f32_e32 v147, 0xbfb8aa3b, v150
	v_exp_f32_e32 v147, v147
	v_mul_f32_e32 v146, v146, v152
	v_mul_f32_e32 v151, v16, v146
	v_mov_b32_e32 v152, v137
	v_add_f32_e32 v146, 1.0, v147
	v_rcp_f32_e32 v170, v146
	v_mov_b32_e32 v146, v22
	v_mov_b32_e32 v147, v140
	v_pk_mul_f32 v[146:147], v[146:147], v[168:169]
	v_mov_b32_dpp v169, v6 row_shl:1 row_mask:0xf bank_mask:0xf bound_ctrl:1
	v_fma_f32 v146, v132, v148, v146
	v_add_f32_e32 v146, v146, v147
	v_add_f32_e32 v148, v144, v146
	v_mul_f32_e32 v146, 0xbfb8aa3b, v148
	v_exp_f32_e32 v168, v146
	v_mov_b32_e32 v146, v23
	v_mov_b32_e32 v147, v141
	v_pk_mul_f32 v[146:147], v[146:147], v[152:153]
	v_mov_b32_dpp v153, v7 row_shl:1 row_mask:0xf bank_mask:0xf bound_ctrl:1
	v_fma_f32 v146, v133, v149, v146
	v_add_f32_e32 v146, v146, v147
	v_add_f32_e32 v146, v145, v146
	v_mul_f32_e32 v147, 0xbfb8aa3b, v146
	v_exp_f32_e32 v147, v147
	v_mul_f32_e32 v149, v150, v170
	v_add_f32_e32 v150, 1.0, v168
	v_rcp_f32_e32 v150, v150
	v_add_f32_e32 v147, 1.0, v147
	v_rcp_f32_e32 v147, v147
	v_mul_f32_e32 v149, v17, v149
	v_mul_f32_e32 v148, v148, v150
	v_mul_f32_e32 v148, v18, v148
	v_mul_f32_e32 v146, v146, v147
	v_mul_f32_e32 v147, v19, v146
	v_cvt_pk_bf16_f32 v146, v151, v149
	v_cvt_pk_bf16_f32 v147, v148, v147
	v_lshl_add_u64 v[148:149], v[166:167], 1, v[180:181]
	global_store_dwordx2 v[148:149], v[146:147], off
	v_mov_b32_dpp v146, v4 row_shr:1 row_mask:0xf bank_mask:0xf bound_ctrl:1
	v_mov_b32_dpp v147, v5 row_shr:1 row_mask:0xf bank_mask:0xf bound_ctrl:1
	v_mov_b32_dpp v151, v5 row_shl:1 row_mask:0xf bank_mask:0xf bound_ctrl:1
	v_mov_b32_dpp v148, v6 row_shr:1 row_mask:0xf bank_mask:0xf bound_ctrl:1
	v_mov_b32_dpp v149, v7 row_shr:1 row_mask:0xf bank_mask:0xf bound_ctrl:1
	s_mov_b64 s[14:15], exec
	v_readlane_b32 s16, v255, 44
	v_readlane_b32 s17, v255, 45
	s_and_b64 s[16:17], s[14:15], s[16:17]
	s_mov_b64 exec, s[16:17]
	v_add_u32_e32 v146, 0xfffffe40, v96
	ds_read_b128 v[146:149], v146
